# w_out transposes split: heavy workgroups keep the even items (one per wave), odd items go to waves 0-3 of workgroups 64..191 after their full attention unit
# baseline (speedup 1.0000x reference)
; #define LAS __attribute__((address_space(3)))
; template <bool PERMUTE>
; __device__ __forceinline__ void p0_transpose_item(const float* W, int K, int N, bf16* WT, LAS float* scr, int item, int lane) {
;     const int nblk = N / 32, kb = item / nblk, nb = item % nblk, k0 = 64 * kb, n0 = 32 * nb;
;     float wv[32];
; #pragma unroll
;     for (int i = 0; i < 32; ++i) wv[i] = __builtin_nontemporal_load(W + (size_t)(k0 + 2 * i + (lane >> 5)) * N + n0 + (lane & 31));
; #pragma unroll
;     for (int i = 0; i < 32; ++i) scr[(2 * i + (lane >> 5)) * 33 + (lane & 31)] = wv[i];
; __global__ void __launch_bounds__(NWAVES * 64, 2) fwd_megakernel(Args a) {
;     ...
;                 {
;                     LAS float* scr = (LAS float*)(lds + wave * 16384);
;                     constexpr int I_OUT = (DMIX / 64) * (DM / 32);
;                     const int it = ((blockIdx.x & 7) * 24 + (l - 8)) * NWAVES + wave;
;                     if (it < I_OUT) p0_transpose_item<false>(a.w_out, DMIX, DM, WOUT, scr, it, lane);
;                     __syncthreads();
.LBB0_274:
	s_or_b64 exec, exec, s[0:1]
	v_and_b32_e32 v134, 31, v230
	v_lshrrev_b32_e32 v0, 5, v231
	v_lshrrev_b32_e32 v127, 3, v231
	v_lshlrev_b32_e32 v1, 3, v230
	s_barrier
	v_and_b32_e32 v130, 56, v1
	v_mov_b32_e32 v131, 0
	v_mul_u32_u24_e32 v123, 0x90, v127
	v_mul_u32_u24_e32 v125, 0x90, v134
	v_lshlrev_b32_e32 v129, 3, v0
	v_lshlrev_b32_e32 v135, 2, v0
	s_and_b32 s33, s98, 7
	s_lshr_b32 s90, s98, 3
	v_lshrrev_b32_e32 v136, 5, v231
	v_lshlrev_b32_e32 v98, 1, v130
	v_readlane_b32 s1, v253, 29
	s_lshl_b32 s0, s98, 4
	s_nop 2
	s_lshl_b32 s1, s1, 1
	s_add_i32 s0, s0, s1
	s_ashr_i32 s1, s0, 31
	s_lshr_b32 s1, s1, 27
	s_add_i32 s1, s0, s1
	s_and_b32 s2, s1, 0x7ffffe0
	s_sub_i32 s0, s0, s2
	s_lshl_b32 s1, s1, 1
	s_lshl_b32 s0, s0, 5
	s_and_b32 s2, s1, 0xffffffc0
	s_ashr_i32 s1, s0, 31
	v_readlane_b32 s12, v253, 4
	v_or_b32_e32 v2, s2, v136
	s_lshl_b64 s[4:5], s[0:1], 2
	v_readlane_b32 s26, v253, 18
	v_readlane_b32 s27, v253, 19
	s_add_u32 s4, s26, s4
	v_or_b32_e32 v8, 2, v2
	v_or_b32_e32 v10, 4, v2
	v_or_b32_e32 v12, 6, v2
	v_or_b32_e32 v14, 8, v2
	v_or_b32_e32 v16, 10, v2
	v_or_b32_e32 v18, 12, v2
	v_or_b32_e32 v20, 14, v2
	s_addc_u32 s5, s27, s5
	v_lshlrev_b32_e32 v0, 2, v134
	v_mov_b32_e32 v1, 0
	v_ashrrev_i32_e32 v3, 31, v2
	v_ashrrev_i32_e32 v9, 31, v8
	v_ashrrev_i32_e32 v11, 31, v10
	v_ashrrev_i32_e32 v13, 31, v12
	v_ashrrev_i32_e32 v15, 31, v14
	v_ashrrev_i32_e32 v17, 31, v16
	v_ashrrev_i32_e32 v19, 31, v18
	v_ashrrev_i32_e32 v21, 31, v20
	v_lshl_add_u64 v[4:5], s[4:5], 0, v[0:1]
	v_lshlrev_b64 v[6:7], 12, v[2:3]
	v_lshlrev_b64 v[8:9], 12, v[8:9]
	v_lshlrev_b64 v[10:11], 12, v[10:11]
	v_lshlrev_b64 v[12:13], 12, v[12:13]
	v_lshlrev_b64 v[14:15], 12, v[14:15]
	v_lshlrev_b64 v[16:17], 12, v[16:17]
	v_lshlrev_b64 v[18:19], 12, v[18:19]
	v_lshlrev_b64 v[20:21], 12, v[20:21]
	v_lshl_add_u64 v[6:7], v[4:5], 0, v[6:7]
	v_lshl_add_u64 v[8:9], v[4:5], 0, v[8:9]
	v_lshl_add_u64 v[10:11], v[4:5], 0, v[10:11]
	v_lshl_add_u64 v[12:13], v[4:5], 0, v[12:13]
	v_lshl_add_u64 v[14:15], v[4:5], 0, v[14:15]
	v_lshl_add_u64 v[16:17], v[4:5], 0, v[16:17]
	v_lshl_add_u64 v[18:19], v[4:5], 0, v[18:19]
	v_lshl_add_u64 v[20:21], v[4:5], 0, v[20:21]
	global_load_dword v22, v[6:7], off nt
	global_load_dword v23, v[8:9], off nt
	global_load_dword v24, v[10:11], off nt
	global_load_dword v25, v[12:13], off nt
	global_load_dword v26, v[14:15], off nt
	global_load_dword v27, v[16:17], off nt
	global_load_dword v28, v[18:19], off nt
	global_load_dword v29, v[20:21], off nt
	v_or_b32_e32 v6, 16, v2
	v_or_b32_e32 v8, 18, v2
	v_or_b32_e32 v10, 20, v2
	v_or_b32_e32 v12, 22, v2
	v_or_b32_e32 v14, 24, v2
	v_or_b32_e32 v16, 26, v2
	v_or_b32_e32 v18, 28, v2
	v_or_b32_e32 v20, 30, v2
	v_ashrrev_i32_e32 v7, 31, v6
	v_ashrrev_i32_e32 v9, 31, v8
	v_ashrrev_i32_e32 v11, 31, v10
	v_ashrrev_i32_e32 v13, 31, v12
	v_ashrrev_i32_e32 v15, 31, v14
	v_ashrrev_i32_e32 v17, 31, v16
	v_ashrrev_i32_e32 v19, 31, v18
	v_ashrrev_i32_e32 v21, 31, v20
	v_lshlrev_b64 v[6:7], 12, v[6:7]
	v_lshlrev_b64 v[8:9], 12, v[8:9]
	v_lshlrev_b64 v[10:11], 12, v[10:11]
	v_lshlrev_b64 v[12:13], 12, v[12:13]
	v_lshlrev_b64 v[14:15], 12, v[14:15]
	v_lshlrev_b64 v[16:17], 12, v[16:17]
	v_lshlrev_b64 v[18:19], 12, v[18:19]
	v_lshlrev_b64 v[20:21], 12, v[20:21]
	v_lshl_add_u64 v[6:7], v[4:5], 0, v[6:7]
	v_lshl_add_u64 v[8:9], v[4:5], 0, v[8:9]
	v_lshl_add_u64 v[10:11], v[4:5], 0, v[10:11]
	v_lshl_add_u64 v[12:13], v[4:5], 0, v[12:13]
	v_lshl_add_u64 v[14:15], v[4:5], 0, v[14:15]
	v_lshl_add_u64 v[16:17], v[4:5], 0, v[16:17]
	v_lshl_add_u64 v[18:19], v[4:5], 0, v[18:19]
	v_lshl_add_u64 v[20:21], v[4:5], 0, v[20:21]
	global_load_dword v30, v[6:7], off nt
	global_load_dword v31, v[8:9], off nt
	global_load_dword v32, v[10:11], off nt
	global_load_dword v33, v[12:13], off nt
	global_load_dword v34, v[14:15], off nt
	global_load_dword v35, v[16:17], off nt
	global_load_dword v36, v[18:19], off nt
	global_load_dword v37, v[20:21], off nt
	v_or_b32_e32 v6, 32, v2
	v_or_b32_e32 v8, 34, v2
	v_or_b32_e32 v10, 36, v2
	v_or_b32_e32 v12, 38, v2
	v_or_b32_e32 v14, 40, v2
	v_or_b32_e32 v16, 42, v2
	v_or_b32_e32 v18, 44, v2
	v_or_b32_e32 v20, 46, v2
	v_ashrrev_i32_e32 v7, 31, v6
	v_ashrrev_i32_e32 v9, 31, v8
	v_ashrrev_i32_e32 v11, 31, v10
	v_ashrrev_i32_e32 v13, 31, v12
	v_ashrrev_i32_e32 v15, 31, v14
	v_ashrrev_i32_e32 v17, 31, v16
	v_ashrrev_i32_e32 v19, 31, v18
	v_ashrrev_i32_e32 v21, 31, v20
	v_lshlrev_b64 v[6:7], 12, v[6:7]
	v_lshlrev_b64 v[8:9], 12, v[8:9]
	v_lshlrev_b64 v[10:11], 12, v[10:11]
	v_lshlrev_b64 v[12:13], 12, v[12:13]
	v_lshlrev_b64 v[14:15], 12, v[14:15]
	v_lshlrev_b64 v[16:17], 12, v[16:17]
	v_lshlrev_b64 v[18:19], 12, v[18:19]
	v_lshlrev_b64 v[20:21], 12, v[20:21]
	v_lshl_add_u64 v[6:7], v[4:5], 0, v[6:7]
	v_lshl_add_u64 v[8:9], v[4:5], 0, v[8:9]
	v_lshl_add_u64 v[10:11], v[4:5], 0, v[10:11]
	v_lshl_add_u64 v[12:13], v[4:5], 0, v[12:13]
	v_lshl_add_u64 v[14:15], v[4:5], 0, v[14:15]
	v_lshl_add_u64 v[16:17], v[4:5], 0, v[16:17]
	v_lshl_add_u64 v[18:19], v[4:5], 0, v[18:19]
	v_lshl_add_u64 v[20:21], v[4:5], 0, v[20:21]
	global_load_dword v38, v[6:7], off nt
	global_load_dword v39, v[8:9], off nt
	global_load_dword v40, v[10:11], off nt
	global_load_dword v41, v[12:13], off nt
	global_load_dword v42, v[14:15], off nt
	global_load_dword v43, v[16:17], off nt
	global_load_dword v44, v[18:19], off nt
	s_nop 0
	global_load_dword v20, v[20:21], off nt
	v_or_b32_e32 v6, 48, v2
	v_or_b32_e32 v8, 50, v2
	v_or_b32_e32 v10, 52, v2
	v_or_b32_e32 v12, 54, v2
	v_or_b32_e32 v14, 56, v2
	v_or_b32_e32 v16, 58, v2
	v_or_b32_e32 v18, 60, v2
	v_or_b32_e32 v2, 62, v2
	v_ashrrev_i32_e32 v7, 31, v6
	v_ashrrev_i32_e32 v9, 31, v8
	v_ashrrev_i32_e32 v11, 31, v10
	v_ashrrev_i32_e32 v3, 31, v2
	v_lshlrev_b64 v[6:7], 12, v[6:7]
	v_lshlrev_b64 v[8:9], 12, v[8:9]
	v_lshlrev_b64 v[10:11], 12, v[10:11]
	v_ashrrev_i32_e32 v13, 31, v12
	v_ashrrev_i32_e32 v15, 31, v14
	v_ashrrev_i32_e32 v17, 31, v16
	v_ashrrev_i32_e32 v19, 31, v18
	v_lshlrev_b64 v[2:3], 12, v[2:3]
	v_lshl_add_u64 v[6:7], v[4:5], 0, v[6:7]
	v_lshl_add_u64 v[8:9], v[4:5], 0, v[8:9]
	v_lshl_add_u64 v[10:11], v[4:5], 0, v[10:11]
	v_lshlrev_b64 v[12:13], 12, v[12:13]
	v_lshlrev_b64 v[14:15], 12, v[14:15]
	v_lshlrev_b64 v[16:17], 12, v[16:17]
	v_lshlrev_b64 v[18:19], 12, v[18:19]
	v_lshl_add_u64 v[2:3], v[4:5], 0, v[2:3]
	v_lshl_add_u64 v[12:13], v[4:5], 0, v[12:13]
	v_lshl_add_u64 v[14:15], v[4:5], 0, v[14:15]
	v_lshl_add_u64 v[16:17], v[4:5], 0, v[16:17]
	v_lshl_add_u64 v[18:19], v[4:5], 0, v[18:19]
	global_load_dword v4, v[6:7], off nt
	global_load_dword v5, v[8:9], off nt
	s_nop 0
	global_load_dword v6, v[10:11], off nt
	global_load_dword v7, v[12:13], off nt
	global_load_dword v8, v[14:15], off nt
	global_load_dword v9, v[16:17], off nt
	s_nop 0
	global_load_dword v10, v[18:19], off nt
	s_nop 0
	global_load_dword v2, v[2:3], off nt
	v_mul_u32_u24_e32 v3, 0x84, v136
	v_readlane_b32 s1, v253, 30
	s_ashr_i32 s3, s2, 31
	s_lshl_b64 s[2:3], s[2:3], 1
	v_add3_u32 v0, s1, v0, v3
	v_add_u32_e32 v3, 0x400, v0
	s_waitcnt vmcnt(30)
; #define LAS __attribute__((address_space(3)))
; #define LDS_WAIT() asm volatile("s_waitcnt lgkmcnt(0)" ::: "memory")
; __device__ __forceinline__ unsigned pk2(float lo, float hi) { return pg8::cvt_pk_bf16(lo, hi); }
; template <bool PERMUTE>
; __device__ __forceinline__ void p0_transpose_item(const float* W, int K, int N, bf16* WT, LAS float* scr, int item, int lane) {
;     ...
;     for (int i = 0; i < 32; ++i) scr[(2 * i + (lane >> 5)) * 33 + (lane & 31)] = wv[i];
;     LDS_WAIT(); asm volatile("" ::: "memory");
;     const int c = lane & 7;
; #pragma unroll
;     for (int j = 0; j < 4; ++j) { const int n = (lane >> 3) + 8 * j; const LAS float* s = scr + (8 * c) * 33 + n;
;         v4u o; o.x = pk2(s[0 * 33], s[1 * 33]); o.y = pk2(s[2 * 33], s[3 * 33]); o.z = pk2(s[4 * 33], s[5 * 33]); o.w = pk2(s[6 * 33], s[7 * 33]);
;         const int dr = PERMUTE ? win_dst_row(n0 + n) : (n0 + n);
;         if (PERMUTE && n0 < 4096) __builtin_nontemporal_store(o, (v4u*)(WT + (size_t)dr * K + k0 + 8 * c));
;         else *(v4u*)(WT + (size_t)dr * K + k0 + 8 * c) = o; }
;     LDS_WAIT(); asm volatile("" ::: "memory");
; }
	ds_write2_b32 v0, v22, v23 offset1:66
	s_waitcnt vmcnt(28)
	ds_write2_b32 v0, v24, v25 offset0:132 offset1:198
	s_waitcnt vmcnt(26)
	ds_write2_b32 v3, v26, v27 offset0:8 offset1:74
	s_waitcnt vmcnt(24)
	ds_write2_b32 v3, v28, v29 offset0:140 offset1:206
	v_add_u32_e32 v3, 0x800, v0
	s_waitcnt vmcnt(22)
	ds_write2_b32 v3, v30, v31 offset0:16 offset1:82
	s_waitcnt vmcnt(20)
	ds_write2_b32 v3, v32, v33 offset0:148 offset1:214
	v_add_u32_e32 v3, 0xc00, v0
	s_waitcnt vmcnt(18)
	ds_write2_b32 v3, v34, v35 offset0:24 offset1:90
	s_waitcnt vmcnt(16)
	ds_write2_b32 v3, v36, v37 offset0:156 offset1:222
	v_add_u32_e32 v3, 0x1000, v0
	s_waitcnt vmcnt(14)
	ds_write2_b32 v3, v38, v39 offset0:32 offset1:98
	s_waitcnt vmcnt(12)
	ds_write2_b32 v3, v40, v41 offset0:164 offset1:230
	v_add_u32_e32 v3, 0x1400, v0
	s_waitcnt vmcnt(10)
	ds_write2_b32 v3, v42, v43 offset0:40 offset1:106
	s_waitcnt vmcnt(8)
	ds_write2_b32 v3, v44, v20 offset0:172 offset1:238
	v_add_u32_e32 v3, 0x1800, v0
	v_add_u32_e32 v0, 0x1c00, v0
	s_waitcnt vmcnt(6)
	ds_write2_b32 v3, v4, v5 offset0:48 offset1:114
	s_waitcnt vmcnt(4)
	ds_write2_b32 v3, v6, v7 offset0:180 offset1:246
	s_waitcnt vmcnt(2)
	ds_write2_b32 v0, v8, v9 offset0:56 offset1:122
	s_waitcnt vmcnt(0)
	ds_write2_b32 v0, v10, v2 offset0:188 offset1:254
	s_waitcnt lgkmcnt(0)
	v_mul_u32_u24_e32 v0, 0x84, v130
	v_lshlrev_b32_e32 v2, 2, v127
	v_add3_u32 v12, s1, v0, v2
	ds_read2_b32 v[2:3], v12 offset1:33
	s_waitcnt lgkmcnt(0)
	v_cvt_pk_bf16_f32 v2, v2, v3
	ds_read2_b32 v[4:5], v12 offset0:66 offset1:99
	s_waitcnt lgkmcnt(0)
	v_cvt_pk_bf16_f32 v3, v4, v5
	ds_read2_b32 v[4:5], v12 offset0:132 offset1:165
	s_waitcnt lgkmcnt(0)
	v_cvt_pk_bf16_f32 v4, v4, v5
	ds_read2_b32 v[6:7], v12 offset0:198 offset1:231
	v_readlane_b32 s4, v253, 48
	v_readlane_b32 s5, v253, 49
	s_add_u32 s2, s4, s2
	s_waitcnt lgkmcnt(0)
	v_cvt_pk_bf16_f32 v5, v6, v7
	v_or_b32_e32 v6, s0, v127
	s_addc_u32 s3, s5, s3
	v_mov_b32_e32 v99, v1
	v_ashrrev_i32_e32 v7, 31, v6
	v_lshl_add_u64 v[8:9], s[2:3], 0, v[98:99]
	v_lshlrev_b64 v[10:11], 12, v[6:7]
	ds_read2_b32 v[0:1], v12 offset0:8 offset1:41
	v_lshl_add_u64 v[10:11], v[8:9], 0, v[10:11]
	global_store_dwordx4 v[10:11], v[2:5], off
	s_waitcnt lgkmcnt(0)
	v_cvt_pk_bf16_f32 v0, v0, v1
	ds_read2_b32 v[2:3], v12 offset0:74 offset1:107
	s_waitcnt lgkmcnt(0)
	v_cvt_pk_bf16_f32 v1, v2, v3
	ds_read2_b32 v[2:3], v12 offset0:140 offset1:173
	s_waitcnt lgkmcnt(0)
	v_cvt_pk_bf16_f32 v2, v2, v3
	ds_read2_b32 v[4:5], v12 offset0:206 offset1:239
	s_waitcnt lgkmcnt(0)
	v_cvt_pk_bf16_f32 v3, v4, v5
	v_or_b32_e32 v4, 8, v6
	v_ashrrev_i32_e32 v5, 31, v4
	v_lshlrev_b64 v[4:5], 12, v[4:5]
	v_lshl_add_u64 v[4:5], v[8:9], 0, v[4:5]
	ds_read2_b32 v[10:11], v12 offset0:16 offset1:49
	global_store_dwordx4 v[4:5], v[0:3], off
	v_readlane_b32 s13, v253, 5
	v_readlane_b32 s14, v253, 6
	s_waitcnt lgkmcnt(0)
	v_cvt_pk_bf16_f32 v0, v10, v11
	ds_read2_b32 v[2:3], v12 offset0:82 offset1:115
	s_waitcnt lgkmcnt(0)
	v_cvt_pk_bf16_f32 v1, v2, v3
	ds_read2_b32 v[2:3], v12 offset0:148 offset1:181
	s_waitcnt lgkmcnt(0)
	v_cvt_pk_bf16_f32 v2, v2, v3
	ds_read2_b32 v[4:5], v12 offset0:214 offset1:247
	s_waitcnt lgkmcnt(0)
	v_cvt_pk_bf16_f32 v3, v4, v5
	v_or_b32_e32 v4, 16, v6
	v_ashrrev_i32_e32 v5, 31, v4
	v_lshlrev_b64 v[4:5], 12, v[4:5]
	v_lshl_add_u64 v[4:5], v[8:9], 0, v[4:5]
	ds_read2_b32 v[10:11], v12 offset0:24 offset1:57
	global_store_dwordx4 v[4:5], v[0:3], off
	v_readlane_b32 s15, v253, 7
	v_readlane_b32 s16, v253, 8
	s_waitcnt lgkmcnt(0)
	v_cvt_pk_bf16_f32 v0, v10, v11
	ds_read2_b32 v[2:3], v12 offset0:90 offset1:123
	s_waitcnt lgkmcnt(0)
	v_cvt_pk_bf16_f32 v1, v2, v3
	ds_read2_b32 v[2:3], v12 offset0:156 offset1:189
	s_waitcnt lgkmcnt(0)
	v_cvt_pk_bf16_f32 v2, v2, v3
	ds_read2_b32 v[4:5], v12 offset0:222 offset1:255
	s_waitcnt lgkmcnt(0)
	v_cvt_pk_bf16_f32 v3, v4, v5
	v_or_b32_e32 v4, 24, v6
	v_ashrrev_i32_e32 v5, 31, v4
	v_lshlrev_b64 v[4:5], 12, v[4:5]
	v_lshl_add_u64 v[4:5], v[8:9], 0, v[4:5]
	global_store_dwordx4 v[4:5], v[0:3], off
	s_waitcnt lgkmcnt(0)
	v_readlane_b32 s17, v253, 9
	v_readlane_b32 s18, v253, 10
	v_readlane_b32 s19, v253, 11
	v_readlane_b32 s20, v253, 12
	v_readlane_b32 s21, v253, 13
	v_readlane_b32 s22, v253, 14
	v_readlane_b32 s23, v253, 15
	v_readlane_b32 s24, v253, 16
	v_readlane_b32 s25, v253, 17
	s_barrier
	s_branch .LBB0_303

; #define LAS __attribute__((address_space(3)))
; template <bool PERMUTE>
; __device__ __forceinline__ void p0_transpose_item(const float* W, int K, int N, bf16* WT, LAS float* scr, int item, int lane) {
;     const int nblk = N / 32, kb = item / nblk, nb = item % nblk, k0 = 64 * kb, n0 = 32 * nb;
;     float wv[32];
; #pragma unroll
;     for (int i = 0; i < 32; ++i) wv[i] = __builtin_nontemporal_load(W + (size_t)(k0 + 2 * i + (lane >> 5)) * N + n0 + (lane & 31));
; #pragma unroll
;     for (int i = 0; i < 32; ++i) scr[(2 * i + (lane >> 5)) * 33 + (lane & 31)] = wv[i];
; __global__ void __launch_bounds__(NWAVES * 64, 2) fwd_megakernel(Args a) {
;     ...
;                 {
;                     LAS float* scr = (LAS float*)(lds + wave * 16384);
;                     constexpr int I_OUT = (DMIX / 64) * (DM / 32);
;                     const int it = ((blockIdx.x & 7) * 24 + (l - 8)) * NWAVES + wave;
;                     if (it < I_OUT) p0_transpose_item<false>(a.w_out, DMIX, DM, WOUT, scr, it, lane);
;                     __syncthreads();
.LBB0_300:
	s_or_b64 exec, exec, s[0:1]
	s_mul_i32 s0, s33, 24
	s_add_i32 s0, s90, s0
	s_lshl_b32 s0, s0, 3
	v_readlane_b32 s1, v253, 29
	s_add_i32 s0, s0, s1
	s_sub_i32 s0, s0, 64
	s_cmpk_gt_i32 s0, 0x3ff
	s_barrier
	s_sub_u32 s0, s98, 64
	s_cmp_gt_u32 s0, 127
	s_cbranch_scc1 .Ltr_skip
	v_readlane_b32 s1, v253, 29
	s_nop 2
	s_cmp_gt_u32 s1, 3
	s_cbranch_scc1 .Ltr_skip
	s_and_b32 s2, s0, 1
	s_lshl_b32 s2, s2, 2
	s_add_i32 s2, s2, s1
	s_lshl_b32 s2, s2, 1
	s_lshr_b32 s0, s0, 1
	s_lshl_b32 s0, s0, 4
	s_add_i32 s0, s0, s2
	s_add_i32 s0, s0, 1
	v_lshrrev_b32_e32 v127, 3, v231
	v_lshlrev_b32_e32 v130, 3, v230
	v_and_b32_e32 v130, 56, v130
	v_and_b32_e32 v134, 31, v230
	v_lshrrev_b32_e32 v136, 5, v231
	v_lshlrev_b32_e32 v98, 1, v130
	s_ashr_i32 s1, s0, 31
	s_lshr_b32 s1, s1, 27
	s_add_i32 s1, s0, s1
	s_and_b32 s2, s1, 0x7ffffe0
	s_sub_i32 s0, s0, s2
	s_lshl_b32 s1, s1, 1
	s_lshl_b32 s0, s0, 5
	s_and_b32 s2, s1, 0xffffffc0
	s_ashr_i32 s1, s0, 31
	v_readlane_b32 s12, v253, 4
	v_or_b32_e32 v2, s2, v136
	s_lshl_b64 s[4:5], s[0:1], 2
	v_readlane_b32 s26, v253, 18
	v_readlane_b32 s27, v253, 19
	s_add_u32 s4, s26, s4
	v_or_b32_e32 v8, 2, v2
	v_or_b32_e32 v10, 4, v2
	v_or_b32_e32 v12, 6, v2
	v_or_b32_e32 v14, 8, v2
	v_or_b32_e32 v16, 10, v2
	v_or_b32_e32 v18, 12, v2
	v_or_b32_e32 v20, 14, v2
	s_addc_u32 s5, s27, s5
	v_lshlrev_b32_e32 v0, 2, v134
	v_mov_b32_e32 v1, 0
	v_ashrrev_i32_e32 v3, 31, v2
	v_ashrrev_i32_e32 v9, 31, v8
	v_ashrrev_i32_e32 v11, 31, v10
	v_ashrrev_i32_e32 v13, 31, v12
	v_ashrrev_i32_e32 v15, 31, v14
	v_ashrrev_i32_e32 v17, 31, v16
	v_ashrrev_i32_e32 v19, 31, v18
	v_ashrrev_i32_e32 v21, 31, v20
	v_lshl_add_u64 v[4:5], s[4:5], 0, v[0:1]
	v_lshlrev_b64 v[6:7], 12, v[2:3]
	v_lshlrev_b64 v[8:9], 12, v[8:9]
	v_lshlrev_b64 v[10:11], 12, v[10:11]
	v_lshlrev_b64 v[12:13], 12, v[12:13]
	v_lshlrev_b64 v[14:15], 12, v[14:15]
	v_lshlrev_b64 v[16:17], 12, v[16:17]
	v_lshlrev_b64 v[18:19], 12, v[18:19]
	v_lshlrev_b64 v[20:21], 12, v[20:21]
	v_lshl_add_u64 v[6:7], v[4:5], 0, v[6:7]
	v_lshl_add_u64 v[8:9], v[4:5], 0, v[8:9]
	v_lshl_add_u64 v[10:11], v[4:5], 0, v[10:11]
	v_lshl_add_u64 v[12:13], v[4:5], 0, v[12:13]
	v_lshl_add_u64 v[14:15], v[4:5], 0, v[14:15]
	v_lshl_add_u64 v[16:17], v[4:5], 0, v[16:17]
	v_lshl_add_u64 v[18:19], v[4:5], 0, v[18:19]
	v_lshl_add_u64 v[20:21], v[4:5], 0, v[20:21]
	global_load_dword v22, v[6:7], off nt
	global_load_dword v23, v[8:9], off nt
	global_load_dword v24, v[10:11], off nt
	global_load_dword v25, v[12:13], off nt
	global_load_dword v26, v[14:15], off nt
	global_load_dword v27, v[16:17], off nt
	global_load_dword v28, v[18:19], off nt
	global_load_dword v29, v[20:21], off nt
	v_or_b32_e32 v6, 16, v2
	v_or_b32_e32 v8, 18, v2
	v_or_b32_e32 v10, 20, v2
	v_or_b32_e32 v12, 22, v2
	v_or_b32_e32 v14, 24, v2
	v_or_b32_e32 v16, 26, v2
	v_or_b32_e32 v18, 28, v2
	v_or_b32_e32 v20, 30, v2
	v_ashrrev_i32_e32 v7, 31, v6
	v_ashrrev_i32_e32 v9, 31, v8
	v_ashrrev_i32_e32 v11, 31, v10
	v_ashrrev_i32_e32 v13, 31, v12
	v_ashrrev_i32_e32 v15, 31, v14
	v_ashrrev_i32_e32 v17, 31, v16
	v_ashrrev_i32_e32 v19, 31, v18
	v_ashrrev_i32_e32 v21, 31, v20
	v_lshlrev_b64 v[6:7], 12, v[6:7]
	v_lshlrev_b64 v[8:9], 12, v[8:9]
	v_lshlrev_b64 v[10:11], 12, v[10:11]
	v_lshlrev_b64 v[12:13], 12, v[12:13]
	v_lshlrev_b64 v[14:15], 12, v[14:15]
	v_lshlrev_b64 v[16:17], 12, v[16:17]
	v_lshlrev_b64 v[18:19], 12, v[18:19]
	v_lshlrev_b64 v[20:21], 12, v[20:21]
	v_lshl_add_u64 v[6:7], v[4:5], 0, v[6:7]
	v_lshl_add_u64 v[8:9], v[4:5], 0, v[8:9]
	v_lshl_add_u64 v[10:11], v[4:5], 0, v[10:11]
	v_lshl_add_u64 v[12:13], v[4:5], 0, v[12:13]
	v_lshl_add_u64 v[14:15], v[4:5], 0, v[14:15]
	v_lshl_add_u64 v[16:17], v[4:5], 0, v[16:17]
	v_lshl_add_u64 v[18:19], v[4:5], 0, v[18:19]
	v_lshl_add_u64 v[20:21], v[4:5], 0, v[20:21]
	global_load_dword v30, v[6:7], off nt
	global_load_dword v31, v[8:9], off nt
	global_load_dword v32, v[10:11], off nt
	global_load_dword v33, v[12:13], off nt
	global_load_dword v34, v[14:15], off nt
	global_load_dword v35, v[16:17], off nt
	global_load_dword v36, v[18:19], off nt
	global_load_dword v37, v[20:21], off nt
	v_or_b32_e32 v6, 32, v2
	v_or_b32_e32 v8, 34, v2
	v_or_b32_e32 v10, 36, v2
	v_or_b32_e32 v12, 38, v2
	v_or_b32_e32 v14, 40, v2
	v_or_b32_e32 v16, 42, v2
	v_or_b32_e32 v18, 44, v2
	v_or_b32_e32 v20, 46, v2
	v_ashrrev_i32_e32 v7, 31, v6
	v_ashrrev_i32_e32 v9, 31, v8
	v_ashrrev_i32_e32 v11, 31, v10
	v_ashrrev_i32_e32 v13, 31, v12
	v_ashrrev_i32_e32 v15, 31, v14
	v_ashrrev_i32_e32 v17, 31, v16
	v_ashrrev_i32_e32 v19, 31, v18
	v_ashrrev_i32_e32 v21, 31, v20
	v_lshlrev_b64 v[6:7], 12, v[6:7]
	v_lshlrev_b64 v[8:9], 12, v[8:9]
	v_lshlrev_b64 v[10:11], 12, v[10:11]
	v_lshlrev_b64 v[12:13], 12, v[12:13]
	v_lshlrev_b64 v[14:15], 12, v[14:15]
	v_lshlrev_b64 v[16:17], 12, v[16:17]
	v_lshlrev_b64 v[18:19], 12, v[18:19]
	v_lshlrev_b64 v[20:21], 12, v[20:21]
	v_lshl_add_u64 v[6:7], v[4:5], 0, v[6:7]
	v_lshl_add_u64 v[8:9], v[4:5], 0, v[8:9]
	v_lshl_add_u64 v[10:11], v[4:5], 0, v[10:11]
	v_lshl_add_u64 v[12:13], v[4:5], 0, v[12:13]
	v_lshl_add_u64 v[14:15], v[4:5], 0, v[14:15]
	v_lshl_add_u64 v[16:17], v[4:5], 0, v[16:17]
	v_lshl_add_u64 v[18:19], v[4:5], 0, v[18:19]
	v_lshl_add_u64 v[20:21], v[4:5], 0, v[20:21]
	global_load_dword v38, v[6:7], off nt
	global_load_dword v39, v[8:9], off nt
	global_load_dword v40, v[10:11], off nt
	global_load_dword v41, v[12:13], off nt
	global_load_dword v42, v[14:15], off nt
	global_load_dword v43, v[16:17], off nt
	global_load_dword v44, v[18:19], off nt
	s_nop 0
	global_load_dword v20, v[20:21], off nt
	v_or_b32_e32 v6, 48, v2
	v_or_b32_e32 v8, 50, v2
	v_or_b32_e32 v10, 52, v2
	v_or_b32_e32 v12, 54, v2
; #define LAS __attribute__((address_space(3)))
; #define LDS_WAIT() asm volatile("s_waitcnt lgkmcnt(0)" ::: "memory")
; __device__ __forceinline__ unsigned pk2(float lo, float hi) { return pg8::cvt_pk_bf16(lo, hi); }
; template <bool PERMUTE>
; __device__ __forceinline__ void p0_transpose_item(const float* W, int K, int N, bf16* WT, LAS float* scr, int item, int lane) {
;     ...
;     for (int i = 0; i < 32; ++i) scr[(2 * i + (lane >> 5)) * 33 + (lane & 31)] = wv[i];
;     LDS_WAIT(); asm volatile("" ::: "memory");
;     const int c = lane & 7;
; #pragma unroll
;     for (int j = 0; j < 4; ++j) { const int n = (lane >> 3) + 8 * j; const LAS float* s = scr + (8 * c) * 33 + n;
;         v4u o; o.x = pk2(s[0 * 33], s[1 * 33]); o.y = pk2(s[2 * 33], s[3 * 33]); o.z = pk2(s[4 * 33], s[5 * 33]); o.w = pk2(s[6 * 33], s[7 * 33]);
;         const int dr = PERMUTE ? win_dst_row(n0 + n) : (n0 + n);
;         if (PERMUTE && n0 < 4096) __builtin_nontemporal_store(o, (v4u*)(WT + (size_t)dr * K + k0 + 8 * c));
;         else *(v4u*)(WT + (size_t)dr * K + k0 + 8 * c) = o; }
;     LDS_WAIT(); asm volatile("" ::: "memory");
; }
	v_or_b32_e32 v14, 56, v2
	v_or_b32_e32 v16, 58, v2
	v_or_b32_e32 v18, 60, v2
	v_or_b32_e32 v2, 62, v2
	v_ashrrev_i32_e32 v7, 31, v6
	v_ashrrev_i32_e32 v9, 31, v8
	v_ashrrev_i32_e32 v11, 31, v10
	v_ashrrev_i32_e32 v3, 31, v2
	v_lshlrev_b64 v[6:7], 12, v[6:7]
	v_lshlrev_b64 v[8:9], 12, v[8:9]
	v_lshlrev_b64 v[10:11], 12, v[10:11]
	v_ashrrev_i32_e32 v13, 31, v12
	v_ashrrev_i32_e32 v15, 31, v14
	v_ashrrev_i32_e32 v17, 31, v16
	v_ashrrev_i32_e32 v19, 31, v18
	v_lshlrev_b64 v[2:3], 12, v[2:3]
	v_lshl_add_u64 v[6:7], v[4:5], 0, v[6:7]
	v_lshl_add_u64 v[8:9], v[4:5], 0, v[8:9]
	v_lshl_add_u64 v[10:11], v[4:5], 0, v[10:11]
	v_lshlrev_b64 v[12:13], 12, v[12:13]
	v_lshlrev_b64 v[14:15], 12, v[14:15]
	v_lshlrev_b64 v[16:17], 12, v[16:17]
	v_lshlrev_b64 v[18:19], 12, v[18:19]
	v_lshl_add_u64 v[2:3], v[4:5], 0, v[2:3]
	v_lshl_add_u64 v[12:13], v[4:5], 0, v[12:13]
	v_lshl_add_u64 v[14:15], v[4:5], 0, v[14:15]
	v_lshl_add_u64 v[16:17], v[4:5], 0, v[16:17]
	v_lshl_add_u64 v[18:19], v[4:5], 0, v[18:19]
	global_load_dword v4, v[6:7], off nt
	global_load_dword v5, v[8:9], off nt
	s_nop 0
	global_load_dword v6, v[10:11], off nt
	global_load_dword v7, v[12:13], off nt
	global_load_dword v8, v[14:15], off nt
	global_load_dword v9, v[16:17], off nt
	s_nop 0
	global_load_dword v10, v[18:19], off nt
	s_nop 0
	global_load_dword v2, v[2:3], off nt
	v_mul_u32_u24_e32 v3, 0x84, v136
	v_readlane_b32 s1, v253, 30
	s_ashr_i32 s3, s2, 31
	s_lshl_b64 s[2:3], s[2:3], 1
	v_add3_u32 v0, s1, v0, v3
	v_add_u32_e32 v3, 0x400, v0
	s_waitcnt vmcnt(30)
	ds_write2_b32 v0, v22, v23 offset1:66
	s_waitcnt vmcnt(28)
	ds_write2_b32 v0, v24, v25 offset0:132 offset1:198
	s_waitcnt vmcnt(26)
	ds_write2_b32 v3, v26, v27 offset0:8 offset1:74
	s_waitcnt vmcnt(24)
	ds_write2_b32 v3, v28, v29 offset0:140 offset1:206
	v_add_u32_e32 v3, 0x800, v0
	s_waitcnt vmcnt(22)
	ds_write2_b32 v3, v30, v31 offset0:16 offset1:82
	s_waitcnt vmcnt(20)
	ds_write2_b32 v3, v32, v33 offset0:148 offset1:214
	v_add_u32_e32 v3, 0xc00, v0
	s_waitcnt vmcnt(18)
	ds_write2_b32 v3, v34, v35 offset0:24 offset1:90
	s_waitcnt vmcnt(16)
	ds_write2_b32 v3, v36, v37 offset0:156 offset1:222
	v_add_u32_e32 v3, 0x1000, v0
	s_waitcnt vmcnt(14)
	ds_write2_b32 v3, v38, v39 offset0:32 offset1:98
	s_waitcnt vmcnt(12)
	ds_write2_b32 v3, v40, v41 offset0:164 offset1:230
	v_add_u32_e32 v3, 0x1400, v0
	s_waitcnt vmcnt(10)
	ds_write2_b32 v3, v42, v43 offset0:40 offset1:106
	s_waitcnt vmcnt(8)
	ds_write2_b32 v3, v44, v20 offset0:172 offset1:238
	v_add_u32_e32 v3, 0x1800, v0
	v_add_u32_e32 v0, 0x1c00, v0
	s_waitcnt vmcnt(6)
	ds_write2_b32 v3, v4, v5 offset0:48 offset1:114
	s_waitcnt vmcnt(4)
	ds_write2_b32 v3, v6, v7 offset0:180 offset1:246
	s_waitcnt vmcnt(2)
	ds_write2_b32 v0, v8, v9 offset0:56 offset1:122
	s_waitcnt vmcnt(0)
	ds_write2_b32 v0, v10, v2 offset0:188 offset1:254
	s_waitcnt lgkmcnt(0)
	v_mul_u32_u24_e32 v0, 0x84, v130
	v_lshlrev_b32_e32 v2, 2, v127
	v_add3_u32 v12, s1, v0, v2
	ds_read2_b32 v[2:3], v12 offset1:33
	s_waitcnt lgkmcnt(0)
	v_cvt_pk_bf16_f32 v2, v2, v3
	ds_read2_b32 v[4:5], v12 offset0:66 offset1:99
	s_waitcnt lgkmcnt(0)
	v_cvt_pk_bf16_f32 v3, v4, v5
	ds_read2_b32 v[4:5], v12 offset0:132 offset1:165
	s_waitcnt lgkmcnt(0)
	v_cvt_pk_bf16_f32 v4, v4, v5
	ds_read2_b32 v[6:7], v12 offset0:198 offset1:231
	v_readlane_b32 s4, v253, 48
	v_readlane_b32 s5, v253, 49
	s_add_u32 s2, s4, s2
	s_waitcnt lgkmcnt(0)
	v_cvt_pk_bf16_f32 v5, v6, v7
	v_or_b32_e32 v6, s0, v127
	s_addc_u32 s3, s5, s3
	v_mov_b32_e32 v99, v1
	v_ashrrev_i32_e32 v7, 31, v6
	v_lshl_add_u64 v[8:9], s[2:3], 0, v[98:99]
	v_lshlrev_b64 v[10:11], 12, v[6:7]
	ds_read2_b32 v[0:1], v12 offset0:8 offset1:41
	v_lshl_add_u64 v[10:11], v[8:9], 0, v[10:11]
	global_store_dwordx4 v[10:11], v[2:5], off
	s_waitcnt lgkmcnt(0)
	v_cvt_pk_bf16_f32 v0, v0, v1
	ds_read2_b32 v[2:3], v12 offset0:74 offset1:107
	s_waitcnt lgkmcnt(0)
	v_cvt_pk_bf16_f32 v1, v2, v3
	ds_read2_b32 v[2:3], v12 offset0:140 offset1:173
	s_waitcnt lgkmcnt(0)
	v_cvt_pk_bf16_f32 v2, v2, v3
	ds_read2_b32 v[4:5], v12 offset0:206 offset1:239
	s_waitcnt lgkmcnt(0)
	v_cvt_pk_bf16_f32 v3, v4, v5
	v_or_b32_e32 v4, 8, v6
	v_ashrrev_i32_e32 v5, 31, v4
	v_lshlrev_b64 v[4:5], 12, v[4:5]
	v_lshl_add_u64 v[4:5], v[8:9], 0, v[4:5]
	ds_read2_b32 v[10:11], v12 offset0:16 offset1:49
	global_store_dwordx4 v[4:5], v[0:3], off
	v_readlane_b32 s13, v253, 5
	v_readlane_b32 s14, v253, 6
	s_waitcnt lgkmcnt(0)
	v_cvt_pk_bf16_f32 v0, v10, v11
	ds_read2_b32 v[2:3], v12 offset0:82 offset1:115
	s_waitcnt lgkmcnt(0)
	v_cvt_pk_bf16_f32 v1, v2, v3
	ds_read2_b32 v[2:3], v12 offset0:148 offset1:181
	s_waitcnt lgkmcnt(0)
	v_cvt_pk_bf16_f32 v2, v2, v3
	ds_read2_b32 v[4:5], v12 offset0:214 offset1:247
	s_waitcnt lgkmcnt(0)
	v_cvt_pk_bf16_f32 v3, v4, v5
	v_or_b32_e32 v4, 16, v6
	v_ashrrev_i32_e32 v5, 31, v4
	v_lshlrev_b64 v[4:5], 12, v[4:5]
	v_lshl_add_u64 v[4:5], v[8:9], 0, v[4:5]
	ds_read2_b32 v[10:11], v12 offset0:24 offset1:57
	global_store_dwordx4 v[4:5], v[0:3], off
	v_readlane_b32 s15, v253, 7
	v_readlane_b32 s16, v253, 8
	s_waitcnt lgkmcnt(0)
	v_cvt_pk_bf16_f32 v0, v10, v11
	ds_read2_b32 v[2:3], v12 offset0:90 offset1:123
	s_waitcnt lgkmcnt(0)
	v_cvt_pk_bf16_f32 v1, v2, v3
	ds_read2_b32 v[2:3], v12 offset0:156 offset1:189
	s_waitcnt lgkmcnt(0)
	v_cvt_pk_bf16_f32 v2, v2, v3
	ds_read2_b32 v[4:5], v12 offset0:222 offset1:255
	s_waitcnt lgkmcnt(0)
	v_cvt_pk_bf16_f32 v3, v4, v5
	v_or_b32_e32 v4, 24, v6
	v_ashrrev_i32_e32 v5, 31, v4
	v_lshlrev_b64 v[4:5], 12, v[4:5]
	v_lshl_add_u64 v[4:5], v[8:9], 0, v[4:5]
	global_store_dwordx4 v[4:5], v[0:3], off
	s_waitcnt lgkmcnt(0)
	v_readlane_b32 s17, v253, 9
	v_readlane_b32 s18, v253, 10
	v_readlane_b32 s19, v253, 11
	v_readlane_b32 s20, v253, 12
	v_readlane_b32 s21, v253, 13
	v_readlane_b32 s22, v253, 14
	v_readlane_b32 s23, v253, 15
	v_readlane_b32 s24, v253, 16
	v_readlane_b32 s25, v253, 17
.Ltr_skip:
	s_branch .LBB0_302
